# v028 + FFN-down residual epilogue: second row-group x loads hoisted above first group's compute (counted vmcnt, no store drain)
# speedup vs baseline: 1.0052x; 1.0052x over previous
; __device__ __forceinline__ u32x4 pack8(const float* f) { u32x4 o; o.x = pk2(f[0], f[1]); o.y = pk2(f[2], f[3]); o.z = pk2(f[4], f[5]); o.w = pk2(f[6], f[7]); return o; }
;     __device__ __forceinline__ void operator()(const Acc& acc, const Unit& u, int wr, int wc, int fr, int fq, LAS const float* rtab) const {
;         const int row0 = u.pm * BM + wr * 64 + fr;
;         const size_t colb = (size_t)u.pn * BM + wc * 32 + 8 * fq;
; #pragma unroll
;         for (int ai = 0; ai < 2; ++ai) {
;             u32x4 xv[4][2];
; #pragma unroll
;             for (int m = 0; m < 4; ++m)
; #pragma unroll
;                 for (int bj = 0; bj < 2; ++bj) xv[m][bj] = *(const u32x4*)(xb + (size_t)(row0 + ai * HALF + m * 16) * DM + colb + bj * HALF);
; #pragma unroll
;             for (int m = 0; m < 4; ++m) {
;                 const int row = row0 + ai * HALF + m * 16;
;                 float s = 0.f;
; #pragma unroll
;                 for (int bj = 0; bj < 2; ++bj) {
;                     const size_t off = (size_t)row * DM + colb + bj * HALF;
;                     float xf[8]; unpack8(xv[m][bj], xf);
;                     float v[8];
; #pragma unroll
;                     for (int j = 0; j < 4; ++j) { v[j] = xf[j] + acc[ai][bj][m][0][j] * alpha; v[4 + j] = xf[4 + j] + acc[ai][bj][m][1][j] * alpha; }
;                     if (fout) { *(f32x4*)(fout + off) = (f32x4){v[0], v[1], v[2], v[3]}; *(f32x4*)(fout + off + 4) = (f32x4){v[4], v[5], v[6], v[7]}; }
;                     else *(u32x4*)(xb + off) = pack8(v);
; #pragma unroll
;                     for (int j = 0; j < 8; ++j) s += v[j] * v[j];
.LBB0_3928:
	v_lshl_add_u32 v190, s9, 8, v65
	s_ashr_i32 s9, s8, 31
	s_lshl_b64 s[10:11], s[8:9], 8
	v_mov_b32_e32 v189, s11
	v_or_b32_e32 v188, s10, v180
	v_ashrrev_i32_e32 v191, 31, v190
	v_lshl_add_u64 v[186:187], v[188:189], 1, s[52:53]
	v_lshlrev_b64 v[130:131], 11, v[190:191]
	v_or_b32_e32 v196, 16, v190
	v_lshl_add_u64 v[130:131], v[186:187], 0, v[130:131]
	v_ashrrev_i32_e32 v197, 31, v196
	global_load_dwordx4 v[206:209], v[130:131], off
	global_load_dwordx4 v[154:157], v[130:131], off offset:256
	v_lshlrev_b64 v[130:131], 11, v[196:197]
	v_or_b32_e32 v194, 32, v190
	v_lshl_add_u64 v[130:131], v[186:187], 0, v[130:131]
	v_ashrrev_i32_e32 v195, 31, v194
	global_load_dwordx4 v[150:153], v[130:131], off
	global_load_dwordx4 v[146:149], v[130:131], off offset:256
	v_lshlrev_b64 v[130:131], 11, v[194:195]
	v_or_b32_e32 v192, 48, v190
	v_lshl_add_u64 v[130:131], v[186:187], 0, v[130:131]
	v_ashrrev_i32_e32 v193, 31, v192
	global_load_dwordx4 v[142:145], v[130:131], off
	global_load_dwordx4 v[138:141], v[130:131], off offset:256
	v_lshlrev_b64 v[130:131], 11, v[192:193]
	v_lshl_add_u64 v[130:131], v[186:187], 0, v[130:131]
	global_load_dwordx4 v[134:137], v[130:131], off
	s_nop 0
	global_load_dwordx4 v[130:133], v[130:131], off offset:256
	v_add_u32_e32 v250, 0x80, v190
	v_ashrrev_i32_e32 v251, 31, v250
	v_lshlrev_b64 v[250:251], 11, v[250:251]
	v_lshl_add_u64 v[250:251], v[186:187], 0, v[250:251]
	global_load_dwordx4 v[216:219], v[250:251], off
	global_load_dwordx4 v[222:225], v[250:251], off offset:256
	v_add_u32_e32 v250, 0x90, v190
	v_ashrrev_i32_e32 v251, 31, v250
	v_lshlrev_b64 v[250:251], 11, v[250:251]
	v_lshl_add_u64 v[250:251], v[186:187], 0, v[250:251]
	global_load_dwordx4 v[226:229], v[250:251], off
	global_load_dwordx4 v[230:233], v[250:251], off offset:256
	v_add_u32_e32 v250, 0xa0, v190
	v_ashrrev_i32_e32 v251, 31, v250
	v_lshlrev_b64 v[250:251], 11, v[250:251]
	v_lshl_add_u64 v[250:251], v[186:187], 0, v[250:251]
	global_load_dwordx4 v[234:237], v[250:251], off
	global_load_dwordx4 v[238:241], v[250:251], off offset:256
	v_add_u32_e32 v250, 0xb0, v190
	v_ashrrev_i32_e32 v251, 31, v250
	v_lshlrev_b64 v[250:251], 11, v[250:251]
	v_lshl_add_u64 v[250:251], v[186:187], 0, v[250:251]
	global_load_dwordx4 v[242:245], v[250:251], off
	global_load_dwordx4 v[246:249], v[250:251], off offset:256
	v_lshlrev_b64 v[200:201], 10, v[190:191]
	v_lshl_add_u64 v[198:199], v[200:201], 0, v[188:189]
	s_andn2_b64 vcc, exec, s[62:63]
	s_waitcnt vmcnt(8) lgkmcnt(0)
	v_lshlrev_b32_e32 v202, 16, v206
	v_and_b32_e32 v203, 0xffff0000, v206
	v_pk_fma_f32 v[122:123], v[122:123], 0.5, v[202:203] op_sel_hi:[1,0,1]
	v_lshlrev_b32_e32 v202, 16, v208
	v_and_b32_e32 v203, 0xffff0000, v208
	v_pk_fma_f32 v[126:127], v[126:127], 0.5, v[202:203] op_sel_hi:[1,0,1]
	v_lshlrev_b32_e32 v202, 16, v207
	v_and_b32_e32 v203, 0xffff0000, v207
	v_pk_fma_f32 v[124:125], v[124:125], 0.5, v[202:203] op_sel_hi:[1,0,1]
	v_lshlrev_b32_e32 v202, 16, v209
	v_and_b32_e32 v203, 0xffff0000, v209
	v_pk_fma_f32 v[128:129], v[128:129], 0.5, v[202:203] op_sel_hi:[1,0,1]
	v_cndmask_b32_e64 v202, 0, 1, s[62:63]
	v_cmp_ne_u32_e64 s[38:39], 1, v202
	v_lshl_add_u64 v[202:203], v[198:199], 2, s[54:55]
	s_cbranch_vccnz .LBB0_3995
	global_store_dwordx4 v[202:203], v[122:125], off
	global_store_dwordx4 v[202:203], v[126:129], off offset:16
	s_cbranch_execnz .LBB0_3931

; __device__ __forceinline__ u32x4 pack8(const float* f) { u32x4 o; o.x = pk2(f[0], f[1]); o.y = pk2(f[2], f[3]); o.z = pk2(f[4], f[5]); o.w = pk2(f[6], f[7]); return o; }
;     __device__ __forceinline__ void operator()(const Acc& acc, const Unit& u, int wr, int wc, int fr, int fq, LAS const float* rtab) const {
;     ...
;         for (int ai = 0; ai < 2; ++ai) {
;             u32x4 xv[4][2];
; #pragma unroll
;             for (int m = 0; m < 4; ++m)
; #pragma unroll
;                 for (int bj = 0; bj < 2; ++bj) xv[m][bj] = *(const u32x4*)(xb + (size_t)(row0 + ai * HALF + m * 16) * DM + colb + bj * HALF);
; #pragma unroll
;             for (int m = 0; m < 4; ++m) {
;                 const int row = row0 + ai * HALF + m * 16;
;                 float s = 0.f;
; #pragma unroll
;                 for (int bj = 0; bj < 2; ++bj) {
;                     const size_t off = (size_t)row * DM + colb + bj * HALF;
;                     float xf[8]; unpack8(xv[m][bj], xf);
;                     float v[8];
; #pragma unroll
;                     for (int j = 0; j < 4; ++j) { v[j] = xf[j] + acc[ai][bj][m][0][j] * alpha; v[4 + j] = xf[4 + j] + acc[ai][bj][m][1][j] * alpha; }
;                     if (fout) { *(f32x4*)(fout + off) = (f32x4){v[0], v[1], v[2], v[3]}; *(f32x4*)(fout + off + 4) = (f32x4){v[4], v[5], v[6], v[7]}; }
;                     else *(u32x4*)(xb + off) = pack8(v);
.LBB0_3960:
	s_or_b64 exec, exec, s[10:11]
	v_add_u32_e32 v100, 0x80, v190
	v_ashrrev_i32_e32 v101, 31, v100
	s_waitcnt lgkmcnt(0)
	v_lshlrev_b64 v[66:67], 11, v[100:101]
	v_add_u32_e32 v98, 0x90, v190
	v_lshl_add_u64 v[66:67], v[186:187], 0, v[66:67]
	v_ashrrev_i32_e32 v99, 31, v98
	s_waitcnt vmcnt(8)
	v_mov_b64_e32 v[106:107], v[216:217]
	v_mov_b64_e32 v[108:109], v[218:219]
	v_mov_b64_e32 v[90:91], v[222:223]
	v_mov_b64_e32 v[92:93], v[224:225]
	v_lshlrev_b64 v[66:67], 11, v[98:99]
	v_add_u32_e32 v96, 0xa0, v190
	v_lshl_add_u64 v[66:67], v[186:187], 0, v[66:67]
	v_ashrrev_i32_e32 v97, 31, v96
	v_mov_b64_e32 v[86:87], v[226:227]
	v_mov_b64_e32 v[88:89], v[228:229]
	v_mov_b64_e32 v[82:83], v[230:231]
	v_mov_b64_e32 v[84:85], v[232:233]
	v_lshlrev_b64 v[66:67], 11, v[96:97]
	v_add_u32_e32 v94, 0xb0, v190
	v_lshl_add_u64 v[66:67], v[186:187], 0, v[66:67]
	v_ashrrev_i32_e32 v95, 31, v94
	v_mov_b64_e32 v[78:79], v[234:235]
	v_mov_b64_e32 v[80:81], v[236:237]
	v_mov_b64_e32 v[74:75], v[238:239]
	v_mov_b64_e32 v[76:77], v[240:241]
	v_lshlrev_b64 v[66:67], 11, v[94:95]
	v_lshl_add_u64 v[66:67], v[186:187], 0, v[66:67]
	v_mov_b64_e32 v[70:71], v[242:243]
	v_mov_b64_e32 v[72:73], v[244:245]
	s_nop 0
	v_mov_b64_e32 v[66:67], v[246:247]
	v_mov_b64_e32 v[68:69], v[248:249]
	v_lshlrev_b64 v[104:105], 10, v[100:101]
	v_lshl_add_u64 v[102:103], v[104:105], 0, v[188:189]
	s_and_b64 vcc, exec, s[38:39]
	s_waitcnt lgkmcnt(0)
	v_lshlrev_b32_e32 v110, 16, v106
	v_and_b32_e32 v111, 0xffff0000, v106
	v_lshlrev_b32_e32 v106, 16, v107
	v_and_b32_e32 v107, 0xffff0000, v107
	v_pk_fma_f32 v[60:61], v[60:61], 0.5, v[110:111] op_sel_hi:[1,0,1]
	v_lshlrev_b32_e32 v110, 16, v108
	v_and_b32_e32 v111, 0xffff0000, v108
	v_pk_fma_f32 v[62:63], v[62:63], 0.5, v[106:107] op_sel_hi:[1,0,1]
	v_lshlrev_b32_e32 v106, 16, v109
	v_and_b32_e32 v107, 0xffff0000, v109
	v_pk_fma_f32 v[56:57], v[56:57], 0.5, v[110:111] op_sel_hi:[1,0,1]
	v_pk_fma_f32 v[58:59], v[58:59], 0.5, v[106:107] op_sel_hi:[1,0,1]
	v_lshl_add_u64 v[106:107], v[102:103], 2, s[54:55]
	s_cbranch_vccnz .LBB0_4003
	global_store_dwordx4 v[106:107], v[60:63], off
	global_store_dwordx4 v[106:107], v[56:59], off offset:16
	s_cbranch_execnz .LBB0_3963
